# M34: M2 + w_in first-round units use write-back stores (final half-unit keeps sc1) + q GEMM epilogue stores write-back (kv GEMM follows in the same phase)
# speedup vs baseline: 1.0162x; 1.0001x over previous
.Lk0_e1:
	v_ashrrev_i32_e32 v140, 1, v141
	v_and_or_b32 v141, v141, 15, s64
	v_and_b32_e32 v140, -8, v140
	s_or_b32 s0, s0, s65
	v_lshl_add_u32 v146, s77, 8, v141
	v_mov_b64_e32 v[142:143], s[8:9]
	v_add_u32_e32 v140, s0, v140
	v_mad_i64_i32 v[142:143], s[0:1], v146, s24, v[142:143]
	v_ashrrev_i32_e32 v141, 31, v140
	s_movk_i32 s0, 0x7c0
	v_lshl_add_u64 v[142:143], v[140:141], 1, v[142:143]
	v_cmp_gt_i32_e32 vcc, s0, v140
	s_and_saveexec_b64 s[0:1], vcc
	s_cbranch_execz .LBB0_482
	v_cvt_pk_bf16_f32 v126, v126, v127
	v_cvt_pk_bf16_f32 v127, v128, v129
	v_cvt_pk_bf16_f32 v128, v122, v123
	v_cvt_pk_bf16_f32 v129, v124, v125
	s_cmp_lg_u64 s[36:37], 0
	s_cbranch_scc1 .Lm3_wb1
	flat_store_dwordx4 v[142:143], v[126:129] sc1
	s_branch .Lm3_j1
.Lm3_wb1:
	flat_store_dwordx4 v[142:143], v[126:129]
.Lm3_j1:
.LBB0_482:
	s_or_b64 exec, exec, s[0:1]
	s_movk_i32 s0, 0x740
	s_cmp_lg_u32 s101, 1
	s_cselect_b32 s0, s0, 0
	v_cmp_gt_i32_e64 s[0:1], s0, v140
	s_and_saveexec_b64 s[6:7], s[0:1]
	s_cbranch_execz .LBB0_484
	v_cvt_pk_bf16_f32 v118, v118, v119
	v_cvt_pk_bf16_f32 v119, v120, v121
	v_cvt_pk_bf16_f32 v120, v110, v111
	v_cvt_pk_bf16_f32 v121, v112, v113
	s_cmp_lg_u64 s[36:37], 0
	s_cbranch_scc1 .Lm3_wb2
	flat_store_dwordx4 v[142:143], v[118:121] offset:256 sc1
	s_branch .Lm3_j2
.Lm3_wb2:
	flat_store_dwordx4 v[142:143], v[118:121] offset:256
.Lm3_j2:
.LBB0_484:
	s_or_b64 exec, exec, s[6:7]
	v_or_b32_e32 v112, 16, v146
	v_mov_b64_e32 v[110:111], s[8:9]
	v_mad_i64_i32 v[110:111], s[6:7], v112, s24, v[110:111]
	v_lshl_add_u64 v[110:111], v[140:141], 1, v[110:111]
	s_and_saveexec_b64 s[6:7], vcc
	s_cbranch_execz .LBB0_486
	v_cvt_pk_bf16_f32 v112, v114, v115
	v_cvt_pk_bf16_f32 v113, v116, v117
	v_cvt_pk_bf16_f32 v114, v106, v107
	v_cvt_pk_bf16_f32 v115, v108, v109
	s_cmp_lg_u64 s[36:37], 0
	s_cbranch_scc1 .Lm3_wb3
	flat_store_dwordx4 v[110:111], v[112:115] sc1
	s_branch .Lm3_j3
.Lm3_wb3:
	flat_store_dwordx4 v[110:111], v[112:115]
.Lm3_j3:
.LBB0_486:
	s_or_b64 exec, exec, s[6:7]
	s_and_saveexec_b64 s[6:7], s[0:1]
	s_cbranch_execz .LBB0_488
	v_cvt_pk_bf16_f32 v102, v102, v103
	v_cvt_pk_bf16_f32 v103, v104, v105
	v_cvt_pk_bf16_f32 v104, v94, v95
	v_cvt_pk_bf16_f32 v105, v96, v97
	s_cmp_lg_u64 s[36:37], 0
	s_cbranch_scc1 .Lm3_wb4
	flat_store_dwordx4 v[110:111], v[102:105] offset:256 sc1
	s_branch .Lm3_j4
.Lm3_wb4:
	flat_store_dwordx4 v[110:111], v[102:105] offset:256
.Lm3_j4:
.LBB0_488:
	s_or_b64 exec, exec, s[6:7]
	v_or_b32_e32 v96, 32, v146
	v_mov_b64_e32 v[94:95], s[8:9]
	v_mad_i64_i32 v[94:95], s[6:7], v96, s24, v[94:95]
	v_lshl_add_u64 v[94:95], v[140:141], 1, v[94:95]
	s_and_saveexec_b64 s[6:7], vcc
	s_cbranch_execz .LBB0_490
	v_cvt_pk_bf16_f32 v96, v98, v99
	v_cvt_pk_bf16_f32 v97, v100, v101
	v_cvt_pk_bf16_f32 v98, v90, v91
	v_cvt_pk_bf16_f32 v99, v92, v93
	s_cmp_lg_u64 s[36:37], 0
	s_cbranch_scc1 .Lm3_wb5
	flat_store_dwordx4 v[94:95], v[96:99] sc1
	s_branch .Lm3_j5
.Lm3_wb5:
	flat_store_dwordx4 v[94:95], v[96:99]
.Lm3_j5:
.LBB0_490:
	s_or_b64 exec, exec, s[6:7]
	s_and_saveexec_b64 s[6:7], s[0:1]
	s_cbranch_execz .LBB0_492
	v_cvt_pk_bf16_f32 v86, v86, v87
	v_cvt_pk_bf16_f32 v87, v88, v89
	v_cvt_pk_bf16_f32 v88, v76, v77
	v_cvt_pk_bf16_f32 v89, v78, v79
	s_cmp_lg_u64 s[36:37], 0
	s_cbranch_scc1 .Lm3_wb6
	flat_store_dwordx4 v[94:95], v[86:89] offset:256 sc1
	s_branch .Lm3_j6
.Lm3_wb6:
	flat_store_dwordx4 v[94:95], v[86:89] offset:256
.Lm3_j6:
.LBB0_492:
	s_or_b64 exec, exec, s[6:7]
	v_or_b32_e32 v78, 48, v146
	v_mov_b64_e32 v[76:77], s[8:9]
	v_mad_i64_i32 v[76:77], s[6:7], v78, s24, v[76:77]
	v_lshl_add_u64 v[76:77], v[140:141], 1, v[76:77]
	s_and_saveexec_b64 s[6:7], vcc
	s_cbranch_execz .LBB0_494
	v_cvt_pk_bf16_f32 v82, v82, v83
	v_cvt_pk_bf16_f32 v83, v84, v85
	v_cvt_pk_bf16_f32 v84, v72, v73
	v_cvt_pk_bf16_f32 v85, v74, v75
	s_cmp_lg_u64 s[36:37], 0
	s_cbranch_scc1 .Lm3_wb7
	flat_store_dwordx4 v[76:77], v[82:85] sc1
	s_branch .Lm3_j7
.Lm3_wb7:
	flat_store_dwordx4 v[76:77], v[82:85]
.Lm3_j7:
.LBB0_494:
	s_or_b64 exec, exec, s[6:7]
	s_and_saveexec_b64 s[6:7], s[0:1]
	s_cbranch_execz .LBB0_496
	v_cvt_pk_bf16_f32 v68, v68, v69
	v_cvt_pk_bf16_f32 v69, v70, v71
	v_cvt_pk_bf16_f32 v70, v64, v65
	v_cvt_pk_bf16_f32 v71, v66, v67
	s_cmp_lg_u64 s[36:37], 0
	s_cbranch_scc1 .Lm3_wb8
	flat_store_dwordx4 v[76:77], v[68:71] offset:256 sc1
	s_branch .Lm3_j8
.Lm3_wb8:
	flat_store_dwordx4 v[76:77], v[68:71] offset:256
.Lm3_j8:
.LBB0_496:
	s_or_b64 exec, exec, s[6:7]
	v_add_u32_e32 v66, 0x80, v146
	v_mov_b64_e32 v[64:65], s[8:9]
	v_mad_i64_i32 v[64:65], s[6:7], v66, s24, v[64:65]
	v_lshl_add_u64 v[64:65], v[140:141], 1, v[64:65]
	s_and_saveexec_b64 s[6:7], vcc
	s_cbranch_execz .LBB0_498
	v_cvt_pk_bf16_f32 v60, v60, v61
	v_cvt_pk_bf16_f32 v61, v62, v63
	v_cvt_pk_bf16_f32 v62, v56, v57
	v_cvt_pk_bf16_f32 v63, v58, v59
	s_cmp_lg_u64 s[36:37], 0
	s_cbranch_scc1 .Lm3_wb9
	flat_store_dwordx4 v[64:65], v[60:63] sc1
	s_branch .Lm3_j9
.Lm3_wb9:
	flat_store_dwordx4 v[64:65], v[60:63]
.Lm3_j9:
.LBB0_498:
	s_or_b64 exec, exec, s[6:7]
	s_and_saveexec_b64 s[6:7], s[0:1]
	s_cbranch_execz .LBB0_500
	v_cvt_pk_bf16_f32 v52, v52, v53
	v_cvt_pk_bf16_f32 v53, v54, v55
	v_cvt_pk_bf16_f32 v54, v44, v45
	v_cvt_pk_bf16_f32 v55, v46, v47
	s_cmp_lg_u64 s[36:37], 0
	s_cbranch_scc1 .Lm3_wb10
	flat_store_dwordx4 v[64:65], v[52:55] offset:256 sc1
	s_branch .Lm3_j10
.Lm3_wb10:
	flat_store_dwordx4 v[64:65], v[52:55] offset:256
.Lm3_j10:
.LBB0_500:
	s_or_b64 exec, exec, s[6:7]
	v_add_u32_e32 v46, 0x90, v146
	v_mov_b64_e32 v[44:45], s[8:9]
	v_mad_i64_i32 v[44:45], s[6:7], v46, s24, v[44:45]
	v_lshl_add_u64 v[44:45], v[140:141], 1, v[44:45]
	s_and_saveexec_b64 s[6:7], vcc
	s_cbranch_execz .LBB0_502
	v_cvt_pk_bf16_f32 v46, v48, v49
	v_cvt_pk_bf16_f32 v47, v50, v51
	v_cvt_pk_bf16_f32 v48, v40, v41
	v_cvt_pk_bf16_f32 v49, v42, v43
	s_cmp_lg_u64 s[36:37], 0
	s_cbranch_scc1 .Lm3_wb11
	flat_store_dwordx4 v[44:45], v[46:49] sc1
	s_branch .Lm3_j11
.Lm3_wb11:
	flat_store_dwordx4 v[44:45], v[46:49]
.Lm3_j11:
.LBB0_502:
	s_or_b64 exec, exec, s[6:7]
	s_and_saveexec_b64 s[6:7], s[0:1]
	s_cbranch_execz .LBB0_504
	v_cvt_pk_bf16_f32 v36, v36, v37
	v_cvt_pk_bf16_f32 v37, v38, v39
	v_cvt_pk_bf16_f32 v38, v28, v29
	v_cvt_pk_bf16_f32 v39, v30, v31
	s_cmp_lg_u64 s[36:37], 0
	s_cbranch_scc1 .Lm3_wb12
	flat_store_dwordx4 v[44:45], v[36:39] offset:256 sc1
	s_branch .Lm3_j12
.Lm3_wb12:
	flat_store_dwordx4 v[44:45], v[36:39] offset:256
.Lm3_j12:
.LBB0_504:
	s_or_b64 exec, exec, s[6:7]
	v_add_u32_e32 v30, 0xa0, v146
	v_mov_b64_e32 v[28:29], s[8:9]
	v_mad_i64_i32 v[28:29], s[6:7], v30, s24, v[28:29]
	v_lshl_add_u64 v[28:29], v[140:141], 1, v[28:29]
	s_and_saveexec_b64 s[6:7], vcc
	s_cbranch_execz .LBB0_506
	v_cvt_pk_bf16_f32 v30, v32, v33
	v_cvt_pk_bf16_f32 v31, v34, v35
	v_cvt_pk_bf16_f32 v32, v24, v25
	v_cvt_pk_bf16_f32 v33, v26, v27
	s_cmp_lg_u64 s[36:37], 0
	s_cbranch_scc1 .Lm3_wb13
	flat_store_dwordx4 v[28:29], v[30:33] sc1
	s_branch .Lm3_j13
.Lm3_wb13:
	flat_store_dwordx4 v[28:29], v[30:33]
.Lm3_j13:
.LBB0_506:
	s_or_b64 exec, exec, s[6:7]
	s_and_saveexec_b64 s[6:7], s[0:1]
	s_cbranch_execz .LBB0_508
	v_cvt_pk_bf16_f32 v20, v20, v21
	v_cvt_pk_bf16_f32 v21, v22, v23
	v_cvt_pk_bf16_f32 v22, v12, v13
	v_cvt_pk_bf16_f32 v23, v14, v15
	s_cmp_lg_u64 s[36:37], 0
	s_cbranch_scc1 .Lm3_wb14
	flat_store_dwordx4 v[28:29], v[20:23] offset:256 sc1
	s_branch .Lm3_j14
.Lm3_wb14:
	flat_store_dwordx4 v[28:29], v[20:23] offset:256
.Lm3_j14:
.LBB0_508:
	s_or_b64 exec, exec, s[6:7]
	v_add_u32_e32 v14, 0xb0, v146
	v_mov_b64_e32 v[12:13], s[8:9]
	v_mad_i64_i32 v[12:13], s[6:7], v14, s24, v[12:13]
	v_lshl_add_u64 v[12:13], v[140:141], 1, v[12:13]
	s_and_saveexec_b64 s[6:7], vcc
	s_cbranch_execnz .LBB0_511
	s_or_b64 exec, exec, s[6:7]
	s_and_saveexec_b64 s[6:7], s[0:1]
	s_cbranch_execnz .LBB0_512

.LBB0_511:
	v_cvt_pk_bf16_f32 v14, v16, v17
	v_cvt_pk_bf16_f32 v15, v18, v19
	v_cvt_pk_bf16_f32 v16, v8, v9
	v_cvt_pk_bf16_f32 v17, v10, v11
	s_cmp_lg_u64 s[36:37], 0
	s_cbranch_scc1 .Lm3_wb15
	flat_store_dwordx4 v[12:13], v[14:17] sc1
	s_branch .Lm3_j15
.Lm3_wb15:
	flat_store_dwordx4 v[12:13], v[14:17]

.LBB0_512:
	v_cvt_pk_bf16_f32 v4, v4, v5
	v_cvt_pk_bf16_f32 v5, v6, v7
	v_cvt_pk_bf16_f32 v6, v0, v1
	v_cvt_pk_bf16_f32 v7, v2, v3
	s_cmp_lg_u64 s[36:37], 0
	s_cbranch_scc1 .Lm3_wb16
	flat_store_dwordx4 v[12:13], v[4:7] offset:256 sc1
	s_branch .Lm3_j16
.Lm3_wb16:
	flat_store_dwordx4 v[12:13], v[4:7] offset:256
.Lm3_j16:
	s_or_b64 exec, exec, s[6:7]
	s_andn2_b64 vcc, exec, s[36:37]
	s_mov_b64 s[0:1], -1
	s_cbranch_vccnz .LBB0_473
.LBB0_513:
	s_andn2_b64 vcc, exec, s[4:5]
	s_cbranch_vccnz .LBB0_472
	s_barrier
	s_branch .LBB0_472
